# v51 + barrier 5 (merge GEMMs -> out-projection) made XCD-local: no L2 write-back / top-level exchange, each XCD proceeds alone
# speedup vs baseline: 1.0085x; 1.0085x over previous
.LBB0_573:
	s_andn2_saveexec_b64 s[8:9], s[8:9]
	s_cbranch_execz .LBB0_582
	s_branch .Lbar5_local
	s_mov_b64 s[10:11], exec
	buffer_wbl2 sc1
	s_waitcnt vmcnt(0)
	v_mbcnt_lo_u32_b32 v0, s10, 0
	v_mbcnt_hi_u32_b32 v0, s11, v0
	v_cmp_eq_u32_e32 vcc, 0, v0
	s_and_saveexec_b64 s[12:13], vcc
	s_cbranch_execz .LBB0_576
	s_bcnt1_i32_b64 s4, s[10:11]
	v_mov_b32_e32 v1, 0xeb5b000
	v_mov_b32_e32 v2, s4
	global_atomic_add v1, v1, v2, s[38:39] offset:3072 sc0

.Lbar5_local:
	v_mov_b32_e32 v0, 0x2000
	v_mov_b32_e32 v1, 5
	global_store_dword v0, v1, s[6:7] sc1
